# DSA attention loop: next block's mask words loaded straight into their holding registers, no vmcnt(0) drain of the K/V/mask prefetch before the block barrier
# speedup vs baseline: 1.0054x; 1.0011x over previous
.LBB0_1281:
	v_mov_b32_e32 v162, v127
	v_pk_add_f32 v[48:49], v[48:49], v[162:163] op_sel_hi:[1,0] neg_lo:[0,1] neg_hi:[0,1]
	v_pk_add_f32 v[50:51], v[50:51], v[162:163] op_sel_hi:[1,0] neg_lo:[0,1] neg_hi:[0,1]
	v_pk_add_f32 v[52:53], v[52:53], v[162:163] op_sel_hi:[1,0] neg_lo:[0,1] neg_hi:[0,1]
	v_pk_add_f32 v[54:55], v[54:55], v[162:163] op_sel_hi:[1,0] neg_lo:[0,1] neg_hi:[0,1]
	v_pk_add_f32 v[56:57], v[56:57], v[162:163] op_sel_hi:[1,0] neg_lo:[0,1] neg_hi:[0,1]
	v_pk_add_f32 v[58:59], v[58:59], v[162:163] op_sel_hi:[1,0] neg_lo:[0,1] neg_hi:[0,1]
	v_pk_add_f32 v[60:61], v[60:61], v[162:163] op_sel_hi:[1,0] neg_lo:[0,1] neg_hi:[0,1]
	v_pk_add_f32 v[62:63], v[62:63], v[162:163] op_sel_hi:[1,0] neg_lo:[0,1] neg_hi:[0,1]
	v_pk_add_f32 v[32:33], v[32:33], v[162:163] op_sel_hi:[1,0] neg_lo:[0,1] neg_hi:[0,1]
	v_pk_add_f32 v[34:35], v[34:35], v[162:163] op_sel_hi:[1,0] neg_lo:[0,1] neg_hi:[0,1]
	v_pk_add_f32 v[36:37], v[36:37], v[162:163] op_sel_hi:[1,0] neg_lo:[0,1] neg_hi:[0,1]
	v_pk_add_f32 v[38:39], v[38:39], v[162:163] op_sel_hi:[1,0] neg_lo:[0,1] neg_hi:[0,1]
	v_pk_add_f32 v[40:41], v[40:41], v[162:163] op_sel_hi:[1,0] neg_lo:[0,1] neg_hi:[0,1]
	v_pk_add_f32 v[42:43], v[42:43], v[162:163] op_sel_hi:[1,0] neg_lo:[0,1] neg_hi:[0,1]
	v_pk_add_f32 v[44:45], v[44:45], v[162:163] op_sel_hi:[1,0] neg_lo:[0,1] neg_hi:[0,1]
	v_pk_add_f32 v[46:47], v[46:47], v[162:163] op_sel_hi:[1,0] neg_lo:[0,1] neg_hi:[0,1]
	v_exp_f32_e32 v128, v32
	v_exp_f32_e32 v129, v33
	v_exp_f32_e32 v34, v34
	v_exp_f32_e32 v35, v35
	v_exp_f32_e32 v36, v36
	v_exp_f32_e32 v37, v37
	v_exp_f32_e32 v38, v38
	v_exp_f32_e32 v39, v39
	v_exp_f32_e32 v40, v40
	v_exp_f32_e32 v41, v41
	v_exp_f32_e32 v42, v42
	v_exp_f32_e32 v43, v43
	v_exp_f32_e32 v44, v44
	v_exp_f32_e32 v45, v45
	v_exp_f32_e32 v46, v46
	v_exp_f32_e32 v47, v47
	v_exp_f32_e32 v48, v48
	v_exp_f32_e32 v49, v49
	v_exp_f32_e32 v50, v50
	v_exp_f32_e32 v51, v51
	v_exp_f32_e32 v52, v52
	v_exp_f32_e32 v53, v53
	v_exp_f32_e32 v54, v54
	v_exp_f32_e32 v55, v55
	v_exp_f32_e32 v56, v56
	v_exp_f32_e32 v57, v57
	v_exp_f32_e32 v58, v58
	v_exp_f32_e32 v59, v59
	v_exp_f32_e32 v60, v60
	v_exp_f32_e32 v61, v61
	v_exp_f32_e32 v62, v62
	v_exp_f32_e32 v63, v63
	v_add_u32_e32 v32, v130, v105
	v_add_u32_e32 v33, 0xa000, v32
	ds_read2_b64 v[136:139], v33 offset0:128 offset1:130
	ds_read2_b64 v[140:143], v33 offset0:132 offset1:134
	v_cvt_pkrtz_f16_f32 v133, v50, v51
	v_cvt_pkrtz_f16_f32 v132, v48, v49
	v_cvt_pkrtz_f16_f32 v134, v52, v53
	v_cvt_pkrtz_f16_f32 v135, v54, v55
	v_add_u32_e32 v32, 0xb000, v32
	s_mov_b64 s[0:1], -1
	s_waitcnt lgkmcnt(1)
	v_mfma_f32_32x32x16_f16 v[16:31], v[136:139], v[132:135], v[16:31]
	ds_read2_b64 v[136:139], v32 offset0:192 offset1:194
	s_cmp_eq_u32 s4, s5
	s_waitcnt lgkmcnt(0)
	v_mfma_f32_32x32x16_f16 v[0:15], v[136:139], v[132:135], v[0:15]
	ds_read2_b64 v[136:139], v32 offset0:196 offset1:198
	v_cvt_pkrtz_f16_f32 v132, v56, v57
	v_cvt_pkrtz_f16_f32 v133, v58, v59
	v_cvt_pkrtz_f16_f32 v134, v60, v61
	v_cvt_pkrtz_f16_f32 v135, v62, v63
	s_waitcnt lgkmcnt(0)
	s_nop 0
	v_mfma_f32_32x32x16_f16 v[0:15], v[136:139], v[132:135], v[0:15]
	ds_read2_b64 v[136:139], v33 offset0:136 offset1:138
	v_mfma_f32_32x32x16_f16 v[16:31], v[140:143], v[132:135], v[16:31]
	v_cvt_pkrtz_f16_f32 v132, v128, v129
	v_cvt_pkrtz_f16_f32 v133, v34, v35
	v_cvt_pkrtz_f16_f32 v134, v36, v37
	v_cvt_pkrtz_f16_f32 v135, v38, v39
	s_waitcnt lgkmcnt(0)
	s_nop 0
	v_mfma_f32_32x32x16_f16 v[16:31], v[136:139], v[132:135], v[16:31]
	ds_read2_b64 v[136:139], v32 offset0:200 offset1:202
	s_waitcnt lgkmcnt(0)
	v_mfma_f32_32x32x16_f16 v[0:15], v[136:139], v[132:135], v[0:15]
	ds_read2_b64 v[136:139], v33 offset0:140 offset1:142
	v_cvt_pkrtz_f16_f32 v132, v40, v41
	v_cvt_pkrtz_f16_f32 v133, v42, v43
	v_cvt_pkrtz_f16_f32 v134, v44, v45
	v_cvt_pkrtz_f16_f32 v135, v46, v47
	s_waitcnt lgkmcnt(0)
	s_nop 0
	v_mfma_f32_32x32x16_f16 v[16:31], v[136:139], v[132:135], v[16:31]
	ds_read2_b64 v[136:139], v32 offset0:204 offset1:206
	s_waitcnt lgkmcnt(0)
	v_mfma_f32_32x32x16_f16 v[0:15], v[136:139], v[132:135], v[0:15]
	s_nop 11
	v_readfirstlane_b32 s8, v0
	s_cbranch_scc1 .LBB0_1285
	v_xor_b32_e32 v123, 1, v123
	s_movk_i32 s0, 0x4800
	v_mul_lo_u32 v32, v123, s0
	s_add_i32 s8, s5, 1
	v_add_u32_e32 v32, v89, v32
	s_waitcnt vmcnt(2)
	ds_write_b128 v32, v[80:83] offset:32768
	s_waitcnt vmcnt(1)
	ds_write_b128 v32, v[84:87] offset:41984
	s_cmp_ge_u32 s8, s4
	s_waitcnt vmcnt(0)
	v_mov_b32_e32 v102, v92
	v_mov_b32_e32 v103, v93
	s_cbranch_scc1 .LBB0_1284
	global_load_dwordx4 v[80:83], v[94:95], off
	global_load_dwordx4 v[84:87], v[96:97], off
	global_load_dwordx2 v[92:93], v[98:99], off
.LBB0_1284:
	s_mov_b64 s[0:1], 0x2000
	v_lshl_add_u64 v[94:95], v[94:95], 0, s[0:1]
	s_mov_b64 s[0:1], 0x80
	v_lshl_add_u64 v[96:97], v[96:97], 0, s[0:1]
	v_lshl_add_u64 v[98:99], v[98:99], 0, 8
	s_mov_b64 s[0:1], 0
	s_waitcnt lgkmcnt(0)
	s_barrier
